# static priority raise (s_setprio 1) for waves 4-7 during the attention phase
# baseline (speedup 1.0000x reference)
; __global__ void __launch_bounds__(512, 2) fwd_kernel(Args a) {
;     ...
;         { PH const float lam = smalls[l];
;           for (int rep = 0; rep < ((PROBE == 1 || ATT_VAR) ? 2 : 1); ++rep)
;           for (int uidx = bid; uidx < 512; uidx += G) { const bool var = ATT_VAR && rep == 0;
;               int bh = uidx >> 5, j = uidx & 31;
;               if (G == 256) { bh = (bid & 7) + 8 * (uidx >> 8); j = bid >> 3; }
;               const int b = bh >> 2, h = bh & 3;
;               attn_qblock(b, h, j * 128, lam, lds, (const bf16_t*)(ar + AR_Q), (const bf16_t*)(ar + AR_K), (const bf16_t*)(ar + AR_VT), (bf16_t*)(ar + AR_MIX), smalls + 16, ssm_ss + (size_t)l * T * 16, var);
.LBB0_1330:
	s_or_b64 exec, exec, s[6:7]
	v_readlane_b32 s4, v255, 8
	s_mov_b64 s[6:7], s[0:1]
	s_mov_b32 s56, s94
	s_mov_b32 s57, s4
	v_mov_b32_e32 v0, v236
	s_waitcnt lgkmcnt(0)
	s_barrier
	v_readfirstlane_b32 s2, v236
	s_nop 0
	s_cmp_ge_u32 s2, 0x100
	s_cbranch_scc0 .Lat_prio_skip
	s_setprio 1
.Lat_prio_skip:
	s_cmpk_gt_i32 s57, 0x1ff
	v_readlane_b32 s5, v255, 9
	s_cbranch_scc1 .LBB0_1383
	s_load_dwordx2 s[4:5], s[6:7], 0x128
	s_lshl_b64 s[6:7], s[48:49], 2
	v_mov_b32_e32 v0, 0x300000
	s_waitcnt lgkmcnt(0)
	s_add_u32 s6, s4, s6
	s_addc_u32 s7, s5, s7
	global_load_dword v237, v0, s[6:7]
	s_and_b32 s58, s57, 7
	s_lshr_b32 s59, s57, 3
	s_add_u32 s10, s4, 0x11000000
	s_addc_u32 s11, s5, 0
	s_add_u32 s60, s4, 0x13000000
	s_addc_u32 s61, s5, 0
	s_add_u32 s62, s4, 0x15000000
	s_addc_u32 s63, s5, 0
	s_add_u32 s12, s4, 0x19000000
	s_addc_u32 s13, s5, 0
	s_add_u32 s14, s4, 0x300040
	s_addc_u32 s15, s5, 0
	s_add_u32 s2, s4, s50
	s_addc_u32 s4, s5, s51
	v_mov_b32_e32 v0, 0x100
	s_add_u32 s16, s2, 0x1e400000
	v_cmp_eq_u32_e64 s[6:7], s56, v0
	s_addc_u32 s17, s4, 0
	s_branch .LBB0_1334

; __device__ __forceinline__ unsigned xb_ld(unsigned* p)              { return __hip_atomic_load(p, __ATOMIC_RELAXED, __HIP_MEMORY_SCOPE_AGENT); }
; __device__ __forceinline__ unsigned xb_add(unsigned* p, unsigned v) { return __hip_atomic_fetch_add(p, v, __ATOMIC_RELAXED, __HIP_MEMORY_SCOPE_AGENT); }
; __device__ __forceinline__ void xcd_barrier_complete(unsigned* bar, unsigned x, unsigned& nloc, unsigned& nx) {
;     ...
;     for (;;) {
;         sum = 0u; cnt = 0u; mine = 0u;
; #pragma unroll
;         for (unsigned j = 0; j < 16; ++j) { const unsigned c = xb_ld(&bar[XB_XCNT(j)]); sum += c; cnt += (c > 0u) ? 1u : 0u; mine = (j == x) ? c : mine; }
; __device__ __forceinline__ void xcd_barrier(const XcdBarrier& b) {
;     asm volatile("s_waitcnt vmcnt(0)" ::: "memory");
;     __syncthreads();
;     if (threadIdx.x == 0) {
;         unsigned* bar = b.bar;
;         __builtin_amdgcn_s_waitcnt(0);
;         unsigned nloc = b.st[0], nx = b.st[1];
;         if (nloc == 0u) { xcd_barrier_complete(bar, b.x, nloc, nx); b.st[0] = nloc; b.st[1] = nx; }
;         const unsigned old = xb_add(&bar[XB_XSUB(b.x)], 1u);
.LBB0_1383:
	s_setprio 0
	s_mov_b64 s[8:9], s[0:1]
	s_getreg_b32 s2, hwreg(HW_REG_XCC_ID, 0, 4)
	s_waitcnt vmcnt(0)
	s_barrier
	s_mov_b64 s[6:7], exec
	v_readlane_b32 s4, v255, 0
	v_readlane_b32 s5, v255, 1
	s_and_b64 s[4:5], s[6:7], s[4:5]
	s_mov_b64 exec, s[4:5]
	s_cbranch_execz .LBB0_1435
	v_readlane_b32 s4, v255, 5
	s_load_dwordx2 s[8:9], s[8:9], 0x128
	s_waitcnt vmcnt(0) expcnt(0) lgkmcnt(0)
	v_mov_b32_e32 v0, s4
	ds_read_b32 v3, v0
	v_readlane_b32 s4, v255, 7
	s_and_b32 s2, s2, 15
	s_waitcnt lgkmcnt(0)
	v_cmp_ne_u32_e32 vcc, 0, v3
	v_mov_b32_e32 v0, s4
	ds_read_b32 v0, v0
	s_cbranch_vccnz .LBB0_1399
	s_add_u32 s10, s8, 0x1200
	s_addc_u32 s11, s9, 0
	s_add_u32 s12, s8, 0x1400
	s_addc_u32 s13, s9, 0
	s_add_u32 s14, s8, 0x1500
	s_addc_u32 s15, s9, 0
	s_add_u32 s16, s8, 0x1600
	s_addc_u32 s17, s9, 0
	s_add_u32 s48, s8, 0x1700
	s_addc_u32 s49, s9, 0
	s_add_u32 s52, s8, 0x1800
	s_addc_u32 s53, s9, 0
	s_add_u32 s54, s8, 0x1900
	s_addc_u32 s55, s9, 0
	s_add_u32 s56, s8, 0x1a00
	s_addc_u32 s57, s9, 0
	s_add_u32 s58, s8, 0x1b00
	s_addc_u32 s59, s9, 0
	s_add_u32 s60, s8, 0x1c00
	s_addc_u32 s61, s9, 0
	s_add_u32 s62, s8, 0x1d00
	s_addc_u32 s63, s9, 0
	s_add_u32 s64, s8, 0x1e00
	s_addc_u32 s65, s9, 0
	s_add_u32 s66, s8, 0x1f00
	s_addc_u32 s67, s9, 0
	s_add_u32 s68, s8, 0x2000
	s_addc_u32 s69, s9, 0
	s_add_u32 s70, s8, 0x2100
	s_addc_u32 s71, s9, 0
	s_add_u32 s72, s8, 0x2200
	s_addc_u32 s73, s9, 0
	s_add_u32 s74, s8, 0x2300
	s_addc_u32 s75, s9, 0
	s_mov_b32 s4, 1
	s_branch .LBB0_1387
